# s9: l-carry kept in its own register (no v_mov on the PV tail), single taken back-edge branch, next-tile K-fragment prefetch spread 2-per-gap over the last two PV MFMA groups
# speedup vs baseline: 1.0375x; 1.0041x over previous
; __device__ __forceinline__ void diff_unit(const bf16_t* __restrict__ proj, bf16_t* __restrict__ mix, float* __restrict__ o1s, const float* __restrict__ g_sub, float lam,
;                                           int rowbase, int T, int h, int qb, char* lds, int widk) {
;     ...
;         float m_reg = 0.f, l_reg = 0.f; f32x16 o[4], negm = f32x16{};
; #pragma unroll
;         for (int d = 0; d < 4; ++d) o[d] = f32x16{};
;     ...
; #pragma unroll
;         for (int t = 0; t < DF_D; ++t) DDMA(t, t);
;         asm volatile("s_waitcnt vmcnt(%0)" :: "n"(3 * (DF_D - 1)) : "memory"); BAR();
;         int ka[4];
; #pragma unroll
;         for (int d0 = 0; d0 < 4; ++d0) ka[d0] = (int)(uintptr_t)K_lds + KSWZ64(r32, (d0 * 16 + hi * 8) * 2);
;     ...
;         if (grp) BAR();
;         int bsl = 0;
; #pragma unroll 1
;         for (int j = 0; j < NT; ++j) {
;             BAR();
;             f32x16 p0, p1;
;             __builtin_amdgcn_s_setprio(1);
;             { const int kb = bsl * DF_KSZ; bf16x8 k0, k1, k2, k3, k4, k5, k6, k7; const int a0 = ka[0] + kb, a1 = ka[1] + kb, a2 = ka[2] + kb, a3 = ka[3] + kb;
;               KRD(k0, a0, 0); KRD(k1, a0, 4096); KRD(k2, a1, 0); KRD(k3, a1, 4096); KRD(k4, a2, 0); KRD(k5, a2, 4096); KRD(k6, a3, 0); KRD(k7, a3, 4096);
;               asm volatile("s_waitcnt lgkmcnt(6)" ::: "memory"); SBAR();
;               asm volatile("v_mfma_f32_32x32x16_bf16 %0, %1, %2, %3" : "=&v"(p0) : "v"(k0), "v"(qr[0]), "v"(negm));
;               asm volatile("v_mfma_f32_32x32x16_bf16 %0, %1, %2, %3" : "=&v"(p1) : "v"(k1), "v"(qr[0]), "v"(negm)); SBAR();
;               asm volatile("s_waitcnt lgkmcnt(4)" ::: "memory"); SBAR();
;               p0 = __builtin_amdgcn_mfma_f32_32x32x16_bf16(k2, qr[1], p0, 0, 0, 0); p1 = __builtin_amdgcn_mfma_f32_32x32x16_bf16(k3, qr[1], p1, 0, 0, 0); SBAR();
;               asm volatile("s_waitcnt lgkmcnt(2)" ::: "memory"); SBAR();
;               p0 = __builtin_amdgcn_mfma_f32_32x32x16_bf16(k4, qr[2], p0, 0, 0, 0); p1 = __builtin_amdgcn_mfma_f32_32x32x16_bf16(k5, qr[2], p1, 0, 0, 0); SBAR();
;               asm volatile("s_waitcnt lgkmcnt(0)" ::: "memory"); SBAR();
;               p0 = __builtin_amdgcn_mfma_f32_32x32x16_bf16(k6, qr[3], p0, 0, 0, 0); p1 = __builtin_amdgcn_mfma_f32_32x32x16_bf16(k7, qr[3], p1, 0, 0, 0); SBAR(); }
;             __builtin_amdgcn_s_setprio(0);
;             float alpha; bf16x8 pa0, pa1, pa2, pa3;
.LBB0_374:
	v_mov_b32_e32 v14, v0
	v_mov_b32_e32 v15, v0
	v_mov_b32_e32 v1, v0
	v_mov_b32_e32 v2, v0
	v_mov_b32_e32 v3, v0
	v_mov_b32_e32 v4, v0
	v_mov_b32_e32 v5, v0
	v_mov_b32_e32 v6, v0
	v_mov_b32_e32 v7, v0
	v_mov_b32_e32 v8, v0
	v_mov_b32_e32 v9, v0
	v_mov_b32_e32 v10, v0
	v_mov_b32_e32 v11, v0
	v_mov_b32_e32 v12, v0
	v_mov_b32_e32 v13, v0
	v_mov_b32_e32 v209, 0
	v_mov_b64_e32 v[30:31], v[14:15]
	v_mov_b64_e32 v[46:47], v[14:15]
	v_mov_b64_e32 v[62:63], v[14:15]
	v_mov_b64_e32 v[78:79], v[14:15]
	s_xor_b64 s[46:47], s[0:1], -1
	v_lshl_add_u64 v[188:189], s[8:9], 1, v[182:183]
	s_mov_b32 s33, 0
	s_mov_b64 s[6:7], 0
	v_mov_b64_e32 v[28:29], v[12:13]
	v_mov_b64_e32 v[26:27], v[10:11]
	v_mov_b64_e32 v[24:25], v[8:9]
	v_mov_b64_e32 v[22:23], v[6:7]
	v_mov_b64_e32 v[20:21], v[4:5]
	v_mov_b64_e32 v[18:19], v[2:3]
	v_mov_b64_e32 v[16:17], v[0:1]
	v_mov_b64_e32 v[44:45], v[12:13]
	v_mov_b64_e32 v[42:43], v[10:11]
	v_mov_b64_e32 v[40:41], v[8:9]
	v_mov_b64_e32 v[38:39], v[6:7]
	v_mov_b64_e32 v[36:37], v[4:5]
	v_mov_b64_e32 v[34:35], v[2:3]
	v_mov_b64_e32 v[32:33], v[0:1]
	v_mov_b64_e32 v[60:61], v[12:13]
	v_mov_b64_e32 v[58:59], v[10:11]
	v_mov_b64_e32 v[56:57], v[8:9]
	v_mov_b64_e32 v[54:55], v[6:7]
	v_mov_b64_e32 v[52:53], v[4:5]
	v_mov_b64_e32 v[50:51], v[2:3]
	v_mov_b64_e32 v[48:49], v[0:1]
	s_mov_b32 s8, 0
	v_mov_b32_e32 v210, 0
	v_mov_b32_e32 v234, 0
	v_mov_b64_e32 v[76:77], v[12:13]
	v_mov_b64_e32 v[74:75], v[10:11]
	v_mov_b64_e32 v[72:73], v[8:9]
	v_mov_b64_e32 v[70:71], v[6:7]
	v_mov_b64_e32 v[68:69], v[4:5]
	v_mov_b64_e32 v[66:67], v[2:3]
	v_mov_b64_e32 v[64:65], v[0:1]
	v_mov_b32_e32 v80, 0
	v_mov_b32_e32 v81, v209
	v_mov_b32_e32 v82, v209
	v_mov_b32_e32 v83, v209
	v_mov_b32_e32 v84, v209
	v_mov_b32_e32 v85, v209
	v_mov_b32_e32 v86, v209
	v_mov_b32_e32 v87, v209
	v_mov_b32_e32 v88, v209
	v_mov_b32_e32 v89, v209
	v_mov_b32_e32 v90, v209
	v_mov_b32_e32 v91, v209
	v_mov_b32_e32 v92, v209
	v_mov_b32_e32 v93, v209
	v_mov_b32_e32 v94, v209
	v_mov_b32_e32 v95, v209
	ds_read_b128 v[236:239], v204
	ds_read_b128 v[240:243], v204 offset:4096
	ds_read_b128 v[244:247], v205
	ds_read_b128 v[248:251], v205 offset:4096
	ds_read_b128 v[216:219], v206
	ds_read_b128 v[220:223], v206 offset:4096
	ds_read_b128 v[224:227], v207
	ds_read_b128 v[228:231], v207 offset:4096
	s_waitcnt vmcnt(0)
.LBB0_375:
	s_barrier
	s_setprio 1
	s_waitcnt lgkmcnt(6)
	v_mfma_f32_32x32x16_bf16 v[112:127], v[236:239], v[128:131], v[80:95]
	v_mfma_f32_32x32x16_bf16 v[96:111], v[240:243], v[128:131], v[80:95]
	s_waitcnt lgkmcnt(4)
	s_nop 0
	v_mfma_f32_32x32x16_bf16 v[112:127], v[244:247], v[132:135], v[112:127]
	v_mfma_f32_32x32x16_bf16 v[96:111], v[248:251], v[132:135], v[96:111]
	s_waitcnt lgkmcnt(2)
	v_mfma_f32_32x32x16_bf16 v[112:127], v[216:219], v[136:139], v[112:127]
	v_mfma_f32_32x32x16_bf16 v[96:111], v[220:223], v[136:139], v[96:111]
	s_waitcnt lgkmcnt(0)
	v_mfma_f32_32x32x16_bf16 v[112:127], v[224:227], v[140:143], v[112:127]
	v_mfma_f32_32x32x16_bf16 v[96:111], v[228:231], v[140:143], v[96:111]
	s_setprio 0
	s_nop 10
	s_cmp_lg_u32 s6, 0
	s_cbranch_scc0 .Ldf_slow
	v_exp_f32_e32 v213, v112
	v_exp_f32_e32 v215, v96
	v_exp_f32_e32 v217, v113
	v_exp_f32_e32 v218, v97
	v_exp_f32_e32 v214, v114
	v_exp_f32_e32 v216, v98
	v_exp_f32_e32 v211, v115
	v_exp_f32_e32 v212, v99
	v_exp_f32_e32 v114, v116
	v_exp_f32_e32 v115, v100
	v_exp_f32_e32 v112, v117
	v_exp_f32_e32 v113, v101
	v_exp_f32_e32 v100, v118
	v_exp_f32_e32 v101, v102
	v_exp_f32_e32 v14, v119
	v_exp_f32_e32 v15, v103
	v_exp_f32_e32 v119, v120
	v_exp_f32_e32 v219, v104
	v_exp_f32_e32 v220, v121
	v_exp_f32_e32 v221, v105
	v_exp_f32_e32 v120, v122
	v_exp_f32_e32 v121, v106
	v_exp_f32_e32 v117, v123
	v_exp_f32_e32 v118, v107
	v_exp_f32_e32 v116, v124
	v_exp_f32_e32 v108, v108
	v_exp_f32_e32 v106, v125
	v_exp_f32_e32 v107, v109
	v_exp_f32_e32 v104, v126
	v_exp_f32_e32 v105, v110
	v_exp_f32_e32 v102, v127
	v_exp_f32_e32 v103, v111
	v_cvt_pk_bf16_f32 v96, v213, v217
	v_cvt_pk_bf16_f32 v97, v214, v211
	v_cvt_pk_bf16_f32 v98, v114, v112
	v_cvt_pk_bf16_f32 v99, v100, v14
	v_cvt_pk_bf16_f32 v10, v119, v220
	v_cvt_pk_bf16_f32 v11, v120, v117
	v_cvt_pk_bf16_f32 v12, v116, v106
	v_cvt_pk_bf16_f32 v13, v104, v102
	v_cvt_pk_bf16_f32 v6, v215, v218
	v_cvt_pk_bf16_f32 v7, v216, v212
	v_cvt_pk_bf16_f32 v8, v115, v113
	v_cvt_pk_bf16_f32 v9, v101, v15
	v_cvt_pk_bf16_f32 v2, v219, v221
	v_cvt_pk_bf16_f32 v3, v121, v118
	v_cvt_pk_bf16_f32 v4, v108, v107
	v_cvt_pk_bf16_f32 v5, v105, v103
	v_add_f32_e32 v109, v217, v213
	v_add_f32_e32 v110, v218, v215
	v_add_f32_e32 v111, v220, v119
	v_add_f32_e32 v119, v221, v219
	v_add_f32_e32 v109, v214, v109
	v_add_f32_e32 v110, v216, v110
	v_add_f32_e32 v111, v120, v111
	v_add_f32_e32 v119, v121, v119
	v_add_f32_e32 v109, v211, v109
	v_add_f32_e32 v110, v212, v110
	v_add_f32_e32 v111, v117, v111
	v_add_f32_e32 v117, v118, v119
	v_add_f32_e32 v109, v114, v109
	v_add_f32_e32 v110, v115, v110
	v_add_f32_e32 v111, v116, v111
	v_add_f32_e32 v108, v108, v117
	v_add_f32_e32 v109, v112, v109
	v_add_f32_e32 v110, v113, v110
	v_add_f32_e32 v106, v106, v111
	v_add_f32_e32 v107, v107, v108
	v_add_f32_e32 v100, v100, v109
	v_add_f32_e32 v101, v101, v110
	v_add_f32_e32 v104, v104, v106
	v_add_f32_e32 v105, v105, v107
	v_add_f32_e32 v14, v14, v100
	v_add_f32_e32 v15, v15, v101
	v_add_f32_e32 v100, v102, v104
	v_add_f32_e32 v101, v103, v105
	v_add_f32_e32 v14, v15, v14
	v_add_f32_e32 v15, v101, v100
	v_add_f32_e32 v14, v15, v14
	v_cmp_gt_f32_e32 vcc, 0x71800000, v14
	s_cmp_lg_u64 vcc, exec
	s_cbranch_scc1 .Ldf_fallback
	v_add_f32_e32 v234, v14, v234

; #define SBAR() __builtin_amdgcn_sched_barrier(0)
; #define PV_MMA(od, L, H) do { od = __builtin_amdgcn_mfma_f32_32x32x16_bf16(pa0, PV_PK(L[0], H[0]), od, 0, 0, 0); od = __builtin_amdgcn_mfma_f32_32x32x16_bf16(pa1, PV_PK(L[1], H[1]), od, 0, 0, 0); \
;     od = __builtin_amdgcn_mfma_f32_32x32x16_bf16(pa2, PV_PK(L[2], H[2]), od, 0, 0, 0); od = __builtin_amdgcn_mfma_f32_32x32x16_bf16(pa3, PV_PK(L[3], H[3]), od, 0, 0, 0); } while (0)
; __device__ __forceinline__ void pv_all_pre(f32x16* o, int vb, bf16x8 pa0, bf16x8 pa1, bf16x8 pa2, bf16x8 pa3) {
;     s16x4 L0[4], H0[4], L1[4], H1[4], L2[4], H2[4], L3[4], H3[4];
;     pv_rd<0>(L0, H0, vb); pv_rd<1>(L1, H1, vb);
;     asm volatile("s_waitcnt lgkmcnt(8)" ::: "memory"); SBAR(); PV_MMA(o[0], L0, H0); SBAR();
;     pv_rd<2>(L2, H2, vb);
;     asm volatile("s_waitcnt lgkmcnt(8)" ::: "memory"); SBAR(); PV_MMA(o[1], L1, H1); SBAR();
;     pv_rd<3>(L3, H3, vb);
;     asm volatile("s_waitcnt lgkmcnt(8)" ::: "memory"); SBAR(); PV_MMA(o[2], L2, H2); SBAR();
;     asm volatile("s_waitcnt lgkmcnt(0)" ::: "memory"); SBAR(); PV_MMA(o[3], L3, H3); SBAR();
; __device__ __forceinline__ void diff_unit(const bf16_t* __restrict__ proj, bf16_t* __restrict__ mix, float* __restrict__ o1s, const float* __restrict__ g_sub, float lam,
;                                           int rowbase, int T, int h, int qb, char* lds, int widk) {
;     ...
;             const int bn = bsl == DF_R - 1 ? 0 : bsl + 1;
;             pv_all_pre(o, vb0 + bsl * SHM_V, pa0, pa1, pa2, pa3);
;             bsl = bn;
.Ldf_skip_dma:
	s_waitcnt lgkmcnt(8)
	v_mfma_f32_32x32x16_bf16 v[64:79], v[96:99], v[100:103], v[64:79]
	v_mfma_f32_32x32x16_bf16 v[64:79], v[10:13], v[104:107], v[64:79]
	v_mfma_f32_32x32x16_bf16 v[64:79], v[6:9], v[108:111], v[64:79]
	v_mfma_f32_32x32x16_bf16 v[64:79], v[2:5], v[112:115], v[64:79]
	ds_read_b64_tr_b16 v[100:101], v1 offset:0x400
	ds_read_b64_tr_b16 v[102:103], v1 offset:0xc00
	ds_read_b64_tr_b16 v[104:105], v1 offset:0x1400
	ds_read_b64_tr_b16 v[106:107], v1 offset:0x1c00
	ds_read_b64_tr_b16 v[108:109], v1 offset:0x2400
	ds_read_b64_tr_b16 v[110:111], v1 offset:0x2c00
	ds_read_b64_tr_b16 v[112:113], v1 offset:0x3400
	ds_read_b64_tr_b16 v[114:115], v1 offset:0x3c00
	s_waitcnt lgkmcnt(8)
	v_mfma_f32_32x32x16_bf16 v[48:63], v[96:99], v[116:119], v[48:63]
	v_mfma_f32_32x32x16_bf16 v[48:63], v[10:13], v[120:123], v[48:63]
	v_mfma_f32_32x32x16_bf16 v[48:63], v[6:9], v[124:127], v[48:63]
	v_mfma_f32_32x32x16_bf16 v[48:63], v[2:5], v[210:213], v[48:63]
	ds_read_b64_tr_b16 v[116:117], v1 offset:0x600
	ds_read_b64_tr_b16 v[118:119], v1 offset:0xe00
	ds_read_b64_tr_b16 v[120:121], v1 offset:0x1600
	ds_read_b64_tr_b16 v[122:123], v1 offset:0x1e00
	ds_read_b64_tr_b16 v[124:125], v1 offset:0x2600
	ds_read_b64_tr_b16 v[126:127], v1 offset:0x2e00
	ds_read_b64_tr_b16 v[210:211], v1 offset:0x3600
	ds_read_b64_tr_b16 v[212:213], v1 offset:0x3e00
	s_waitcnt lgkmcnt(8)
	s_lshl_b32 s99, s0, 13
	v_mfma_f32_32x32x16_bf16 v[32:47], v[96:99], v[100:103], v[32:47]
	v_add_u32_e32 v252, s99, v204
	v_add_u32_e32 v255, s99, v205
	v_mfma_f32_32x32x16_bf16 v[32:47], v[10:13], v[104:107], v[32:47]
	ds_read_b128 v[236:239], v252
	ds_read_b128 v[240:243], v252 offset:4096
	v_mfma_f32_32x32x16_bf16 v[32:47], v[6:9], v[108:111], v[32:47]
	ds_read_b128 v[244:247], v255
	ds_read_b128 v[248:251], v255 offset:4096
	v_mfma_f32_32x32x16_bf16 v[32:47], v[2:5], v[112:115], v[32:47]
	v_add_u32_e32 v235, s99, v206
	v_add_u32_e32 v254, s99, v207
	s_waitcnt lgkmcnt(4)
	v_mfma_f32_32x32x16_bf16 v[16:31], v[96:99], v[116:119], v[16:31]
	ds_read_b128 v[216:219], v235
	ds_read_b128 v[220:223], v235 offset:4096
	v_mfma_f32_32x32x16_bf16 v[16:31], v[10:13], v[120:123], v[16:31]
	ds_read_b128 v[224:227], v254
	ds_read_b128 v[228:231], v254 offset:4096
	v_mfma_f32_32x32x16_bf16 v[16:31], v[6:9], v[124:127], v[16:31]
	v_mfma_f32_32x32x16_bf16 v[16:31], v[2:5], v[210:213], v[16:31]
	s_add_i32 s8, s8, 1
	s_add_u32 s6, s6, 0xc0000
	s_addc_u32 s7, s7, 0
	s_mov_b32 s33, s0
	s_cmp_lg_u32 s8, s66
	s_cbranch_scc1 .LBB0_375
	s_branch .LBB0_395

; #define SBAR() __builtin_amdgcn_sched_barrier(0)
; __device__ __forceinline__ void softmax_rel(f32x16& p0, f32x16& p1, float& m_reg, float& l_reg, f32x16& negm, float& alpha, bool first, bf16x8& pa0, bf16x8& pa1, bf16x8& pa2, bf16x8& pa3) {
;     ...
;     float ps0 = p0[0], ps1 = p1[0], ps2 = p0[8], ps3 = p1[8];
; #pragma unroll
;     for (int r = 1; r < 8; ++r) { ps0 += p0[r]; ps1 += p1[r]; ps2 += p0[8 + r]; ps3 += p1[8 + r]; }
;     l_reg = l_reg * alpha + ((ps0 + ps1) + (ps2 + ps3));
; __device__ __forceinline__ void diff_unit(const bf16_t* __restrict__ proj, bf16_t* __restrict__ mix, float* __restrict__ o1s, const float* __restrict__ g_sub, float lam,
;                                           int rowbase, int T, int h, int qb, char* lds, int widk) {
;     ...
;             { const int kb = bsl * DF_KSZ; bf16x8 k0, k1, k2, k3, k4, k5, k6, k7; const int a0 = ka[0] + kb, a1 = ka[1] + kb, a2 = ka[2] + kb, a3 = ka[3] + kb;
;               KRD(k0, a0, 0); KRD(k1, a0, 4096); KRD(k2, a1, 0); KRD(k3, a1, 4096); KRD(k4, a2, 0); KRD(k5, a2, 4096); KRD(k6, a3, 0); KRD(k7, a3, 4096);
;               asm volatile("s_waitcnt lgkmcnt(6)" ::: "memory"); SBAR();
;               asm volatile("v_mfma_f32_32x32x16_bf16 %0, %1, %2, %3" : "=&v"(p0) : "v"(k0), "v"(qr[0]), "v"(negm));
;               asm volatile("v_mfma_f32_32x32x16_bf16 %0, %1, %2, %3" : "=&v"(p1) : "v"(k1), "v"(qr[0]), "v"(negm)); SBAR();
;               asm volatile("s_waitcnt lgkmcnt(4)" ::: "memory"); SBAR();
;               p0 = __builtin_amdgcn_mfma_f32_32x32x16_bf16(k2, qr[1], p0, 0, 0, 0); p1 = __builtin_amdgcn_mfma_f32_32x32x16_bf16(k3, qr[1], p1, 0, 0, 0); SBAR();
;               asm volatile("s_waitcnt lgkmcnt(2)" ::: "memory"); SBAR();
;               p0 = __builtin_amdgcn_mfma_f32_32x32x16_bf16(k4, qr[2], p0, 0, 0, 0); p1 = __builtin_amdgcn_mfma_f32_32x32x16_bf16(k5, qr[2], p1, 0, 0, 0); SBAR();
;               asm volatile("s_waitcnt lgkmcnt(0)" ::: "memory"); SBAR();
;               p0 = __builtin_amdgcn_mfma_f32_32x32x16_bf16(k6, qr[3], p0, 0, 0, 0); p1 = __builtin_amdgcn_mfma_f32_32x32x16_bf16(k7, qr[3], p1, 0, 0, 0); SBAR(); }
;     ...
;         asm volatile("s_waitcnt lgkmcnt(0)" ::: "memory");
;         if (!grp) BAR();
;         BAR();
;     ...
;         { auto rr = __builtin_amdgcn_permlane32_swap(__float_as_uint(l_reg), __float_as_uint(l_reg), false, false); l_reg = __uint_as_float(rr[0]) + __uint_as_float(rr[1]); }
.LBB0_384:
	v_add_f32_e32 v109, v217, v213
	v_add_f32_e32 v110, v218, v215
	v_add_f32_e32 v111, v220, v119
	v_add_f32_e32 v119, v221, v219
	v_add_f32_e32 v109, v214, v109
	v_add_f32_e32 v110, v216, v110
	v_add_f32_e32 v111, v120, v111
	v_add_f32_e32 v119, v121, v119
	v_add_f32_e32 v109, v211, v109
	v_add_f32_e32 v110, v212, v110
	v_add_f32_e32 v111, v117, v111
	v_add_f32_e32 v117, v118, v119
	v_add_f32_e32 v109, v114, v109
	v_add_f32_e32 v110, v115, v110
	v_add_f32_e32 v111, v116, v111
	v_add_f32_e32 v108, v108, v117
	v_add_f32_e32 v109, v112, v109
	v_add_f32_e32 v110, v113, v110
	v_add_f32_e32 v106, v106, v111
	v_add_f32_e32 v107, v107, v108
	v_add_f32_e32 v100, v100, v109
	v_add_f32_e32 v101, v101, v110
	v_add_f32_e32 v104, v104, v106
	v_add_f32_e32 v105, v105, v107
	v_add_f32_e32 v14, v14, v100
	v_add_f32_e32 v15, v15, v101
	v_add_f32_e32 v100, v102, v104
	v_add_f32_e32 v101, v103, v105
	v_add_f32_e32 v14, v15, v14
	v_add_f32_e32 v15, v101, v100
	v_add_f32_e32 v14, v15, v14
	v_fma_f32 v234, v234, v1, v14
	s_branch .Ldf_tail
.Ldf_fallback:
	s_lshl_b32 s98, s33, 13
	v_add_u32_e32 v252, s98, v204
	v_add_u32_e32 v255, s98, v205
	v_add_u32_e32 v235, s98, v206
	v_add_u32_e32 v254, s98, v207
	ds_read_b128 v[236:239], v252
	ds_read_b128 v[240:243], v252 offset:4096
	ds_read_b128 v[244:247], v255
	ds_read_b128 v[248:251], v255 offset:4096
	ds_read_b128 v[216:219], v235
	ds_read_b128 v[220:223], v235 offset:4096
	ds_read_b128 v[224:227], v254
	ds_read_b128 v[228:231], v254 offset:4096
	s_waitcnt lgkmcnt(0)
	v_mfma_f32_32x32x16_bf16 v[112:127], v[236:239], v[128:131], v[80:95]
	v_mfma_f32_32x32x16_bf16 v[96:111], v[240:243], v[128:131], v[80:95]
	v_mfma_f32_32x32x16_bf16 v[112:127], v[244:247], v[132:135], v[112:127]
	v_mfma_f32_32x32x16_bf16 v[96:111], v[248:251], v[132:135], v[96:111]
	v_mfma_f32_32x32x16_bf16 v[112:127], v[216:219], v[136:139], v[112:127]
	v_mfma_f32_32x32x16_bf16 v[96:111], v[220:223], v[136:139], v[96:111]
	v_mfma_f32_32x32x16_bf16 v[112:127], v[224:227], v[140:143], v[112:127]
	v_mfma_f32_32x32x16_bf16 v[96:111], v[228:231], v[140:143], v[96:111]
	s_nop 11
	s_branch .Ldf_slow
.LBB0_395:
	v_mov_b32_e32 v14, v234
	s_waitcnt lgkmcnt(0)
	s_and_b64 vcc, exec, s[42:43]
	s_cbranch_vccz .LBB0_397
	s_barrier
